# out-proj residual epilogue also issues its residual loads as two bursts of 8
# baseline (speedup 1.0000x reference)
.LBB0_831:
	s_lshl_b32 s9, s21, 8
	s_add_i32 s9, s9, s55
	v_and_or_b32 v228, v124, 15, s9
	v_lshlrev_b64 v[232:233], 1, v[224:225]
	v_ashrrev_i32_e32 v229, 31, v228
	v_lshl_add_u64 v[122:123], s[88:89], 0, v[232:233]
	v_lshlrev_b64 v[236:237], 11, v[228:229]
	v_lshlrev_b32_e32 v212, 2, v124
	v_cmp_gt_u32_e32 vcc, 16, v124
	v_lshl_add_u64 v[124:125], v[122:123], 0, v[236:237]
	global_load_dwordx4 v[206:209], v[124:125], off
	global_load_dwordx4 v[202:205], v[124:125], off offset:256
	v_or_b32_e32 v210, 16, v228
	v_ashrrev_i32_e32 v211, 31, v210
	v_lshlrev_b64 v[124:125], 11, v[210:211]
	v_or_b32_e32 v246, 32, v228
	v_lshl_add_u64 v[124:125], v[122:123], 0, v[124:125]
	v_ashrrev_i32_e32 v247, 31, v246
	global_load_dwordx4 v[198:201], v[124:125], off
	global_load_dwordx4 v[194:197], v[124:125], off offset:256
	v_lshlrev_b64 v[124:125], 11, v[246:247]
	v_or_b32_e32 v242, 48, v228
	v_lshl_add_u64 v[124:125], v[122:123], 0, v[124:125]
	v_ashrrev_i32_e32 v243, 31, v242
	global_load_dwordx4 v[190:193], v[124:125], off
	global_load_dwordx4 v[186:189], v[124:125], off offset:256
	v_lshlrev_b64 v[124:125], 11, v[242:243]
	v_add_u32_e32 v238, 0x80, v228
	v_lshl_add_u64 v[124:125], v[122:123], 0, v[124:125]
	v_ashrrev_i32_e32 v239, 31, v238
	global_load_dwordx4 v[182:185], v[124:125], off
	global_load_dwordx4 v[178:181], v[124:125], off offset:256
	v_xor_b32_e32 v249, 64, v212
	v_xor_b32_e32 v248, 0x80, v212
	s_lshl_b32 s10, s20, 2
	s_ashr_i32 s11, s10, 31
	s_waitcnt vmcnt(7)
	v_lshlrev_b64 v[124:125], 11, v[238:239]
	v_add_u32_e32 v234, 0x90, v228
	v_lshl_add_u64 v[124:125], v[122:123], 0, v[124:125]
	v_ashrrev_i32_e32 v235, 31, v234
	global_load_dwordx4 v[166:169], v[124:125], off
	global_load_dwordx4 v[162:165], v[124:125], off offset:256
	v_lshlrev_b64 v[124:125], 11, v[234:235]
	v_add_u32_e32 v230, 0xa0, v228
	v_lshl_add_u64 v[124:125], v[122:123], 0, v[124:125]
	v_ashrrev_i32_e32 v231, 31, v230
	global_load_dwordx4 v[158:161], v[124:125], off
	global_load_dwordx4 v[154:157], v[124:125], off offset:256
	v_lshlrev_b64 v[124:125], 11, v[230:231]
	v_add_u32_e32 v226, 0xb0, v228
	v_lshl_add_u64 v[124:125], v[122:123], 0, v[124:125]
	v_ashrrev_i32_e32 v227, 31, v226
	global_load_dwordx4 v[150:153], v[124:125], off
	global_load_dwordx4 v[138:141], v[124:125], off offset:256
	v_lshlrev_b64 v[124:125], 11, v[226:227]
	v_lshl_add_u64 v[122:123], v[122:123], 0, v[124:125]
	global_load_dwordx4 v[130:133], v[122:123], off
	s_nop 0
	global_load_dwordx4 v[122:125], v[122:123], off offset:256
	v_lshlrev_b32_e32 v212, 16, v206
	v_and_b32_e32 v213, 0xffff0000, v206
	v_lshlrev_b32_e32 v206, 16, v207
	v_and_b32_e32 v207, 0xffff0000, v207
	v_pk_add_f32 v[176:177], v[176:177], v[206:207]
	v_lshlrev_b32_e32 v206, 16, v208
	v_and_b32_e32 v207, 0xffff0000, v208
	v_pk_add_f32 v[174:175], v[174:175], v[212:213]
	v_pk_add_f32 v[170:171], v[170:171], v[206:207]
	v_lshlrev_b32_e32 v206, 16, v209
	v_and_b32_e32 v207, 0xffff0000, v209
	v_pk_add_f32 v[174:175], v[106:107], v[174:175]
	v_pk_add_f32 v[170:171], v[94:95], v[170:171]
	v_pk_add_f32 v[172:173], v[172:173], v[206:207]
	v_pk_add_f32 v[176:177], v[108:109], v[176:177]
	v_pk_add_f32 v[206:207], v[96:97], v[172:173]
	v_cvt_pk_bf16_f32 v172, v174, v175
	v_cvt_pk_bf16_f32 v174, v170, v171
	v_lshl_add_u64 v[170:171], s[88:89], 0, v[236:237]
	v_cvt_pk_bf16_f32 v173, v176, v177
	v_cvt_pk_bf16_f32 v175, v206, v207
	v_lshl_add_u64 v[170:171], v[170:171], 0, v[232:233]
	global_store_dwordx4 v[170:171], v[172:175], off
	v_lshlrev_b32_e32 v176, 16, v172
	v_lshlrev_b32_e32 v177, 16, v173
	v_and_b32_e32 v172, 0xffff0000, v172
	v_and_b32_e32 v173, 0xffff0000, v173
	v_mul_f32_e32 v172, v172, v172
	v_mul_f32_e32 v173, v173, v173
	v_lshlrev_b32_e32 v206, 16, v174
	v_and_b32_e32 v174, 0xffff0000, v174
	v_fmac_f32_e32 v172, v176, v176
	v_fmac_f32_e32 v173, v177, v177
	v_add_f32_e32 v172, v172, v173
	v_mul_f32_e32 v173, v174, v174
	v_lshlrev_b32_e32 v207, 16, v175
	v_and_b32_e32 v175, 0xffff0000, v175
	v_fmac_f32_e32 v173, v206, v206
	v_add_f32_e32 v172, v173, v172
	v_mul_f32_e32 v173, v175, v175
	v_fmac_f32_e32 v173, v207, v207
	v_add_f32_e32 v176, v173, v172
	s_waitcnt vmcnt(15)
	v_lshlrev_b32_e32 v172, 16, v202
	v_and_b32_e32 v173, 0xffff0000, v202
	v_pk_add_f32 v[146:147], v[146:147], v[172:173]
	v_lshlrev_b32_e32 v172, 16, v203
	v_and_b32_e32 v173, 0xffff0000, v203
	v_pk_add_f32 v[148:149], v[148:149], v[172:173]
	v_lshlrev_b32_e32 v172, 16, v204
	v_and_b32_e32 v173, 0xffff0000, v204
	v_pk_add_f32 v[142:143], v[142:143], v[172:173]
	v_pk_add_f32 v[146:147], v[102:103], v[146:147]
	v_pk_add_f32 v[172:173], v[90:91], v[142:143]
	v_lshlrev_b32_e32 v142, 16, v205
	v_and_b32_e32 v143, 0xffff0000, v205
	v_pk_add_f32 v[142:143], v[144:145], v[142:143]
	v_pk_add_f32 v[148:149], v[104:105], v[148:149]
	v_pk_add_f32 v[174:175], v[92:93], v[142:143]
	v_cvt_pk_bf16_f32 v142, v146, v147
	v_cvt_pk_bf16_f32 v143, v148, v149
	v_cvt_pk_bf16_f32 v144, v172, v173
	v_cvt_pk_bf16_f32 v145, v174, v175
	global_store_dwordx4 v[170:171], v[142:145], off offset:256
	v_lshlrev_b32_e32 v146, 16, v142
	v_lshlrev_b32_e32 v147, 16, v143
	v_and_b32_e32 v142, 0xffff0000, v142
	v_and_b32_e32 v143, 0xffff0000, v143
	v_mul_f32_e32 v142, v142, v142
	v_fmac_f32_e32 v142, v146, v146
	v_mul_f32_e32 v143, v143, v143
	v_lshlrev_b32_e32 v148, 16, v144
	v_and_b32_e32 v144, 0xffff0000, v144
	v_add_f32_e32 v142, v142, v176
	v_fmac_f32_e32 v143, v147, v147
	v_add_f32_e32 v142, v143, v142
	v_mul_f32_e32 v143, v144, v144
	v_lshlrev_b32_e32 v149, 16, v145
	v_and_b32_e32 v145, 0xffff0000, v145
	v_fmac_f32_e32 v143, v148, v148
	v_add_f32_e32 v142, v143, v142
	v_mul_f32_e32 v143, v145, v145
	v_fmac_f32_e32 v143, v149, v149
	v_add_f32_e32 v142, v143, v142
	ds_bpermute_b32 v143, v249, v142
	s_waitcnt lgkmcnt(0)
	v_add_f32_e32 v142, v142, v143
	ds_bpermute_b32 v143, v248, v142
	s_and_saveexec_b64 s[42:43], vcc
	s_cbranch_execz .LBB0_833
	v_lshlrev_b64 v[144:145], 6, v[228:229]
	v_lshl_add_u64 v[144:145], s[68:69], 0, v[144:145]
	v_lshl_add_u64 v[144:145], s[10:11], 2, v[144:145]
	s_lshl_b32 s76, s54, 2
	v_lshl_add_u64 v[144:145], v[144:145], 0, s[76:77]
	s_waitcnt lgkmcnt(0)
	v_add_f32_e32 v142, v142, v143
	global_store_dword v[144:145], v142, off
